# SSD prompt unit: transposed LDS reads de-serialised (12 reads in flight per wait instead of 1); on top of v9
# baseline (speedup 1.0000x reference)
.LBB0_356:
	ds_read_b128 v[74:77], v134
	ds_read_b128 v[78:81], v135
	s_andn2_b64 vcc, exec, s[86:87]
	s_waitcnt lgkmcnt(1)
	v_sub_f32_e32 v74, v218, v74
	v_mul_f32_e32 v74, 0x3fb8aa3b, v74
	v_exp_f32_e32 v74, v74
	s_nop 0
	v_mul_f32_e32 v54, v54, v74
	s_waitcnt lgkmcnt(0)
	v_mul_f32_e32 v54, v78, v54
	v_cndmask_b32_e64 v219, v54, 0, s[6:7]
	v_sub_f32_e32 v54, v218, v75
	v_mul_f32_e32 v54, 0x3fb8aa3b, v54
	v_exp_f32_e32 v54, v54
	s_nop 0
	v_mul_f32_e32 v54, v55, v54
	v_mul_f32_e32 v54, v79, v54
	v_cndmask_b32_e64 v220, 0, v54, s[8:9]
	v_sub_f32_e32 v54, v218, v76
	v_sub_f32_e32 v55, v218, v77
	v_mul_f32_e32 v54, 0x3fb8aa3b, v54
	v_mul_f32_e32 v55, 0x3fb8aa3b, v55
	v_exp_f32_e32 v54, v54
	v_exp_f32_e32 v55, v55
	s_nop 0
	v_pk_mul_f32 v[54:55], v[56:57], v[54:55]
	s_nop 0
	v_pk_mul_f32 v[78:79], v[80:81], v[54:55]
	ds_read_b128 v[54:57], v136
	ds_read_b128 v[74:77], v137
	s_waitcnt lgkmcnt(1)
	v_sub_f32_e32 v54, v218, v54
	v_mul_f32_e32 v54, 0x3fb8aa3b, v54
	v_exp_f32_e32 v54, v54
	s_nop 0
	v_mul_f32_e32 v50, v50, v54
	s_waitcnt lgkmcnt(0)
	v_mul_f32_e32 v50, v74, v50
	v_cndmask_b32_e64 v74, v50, 0, s[14:15]
	v_sub_f32_e32 v50, v218, v55
	v_mul_f32_e32 v50, 0x3fb8aa3b, v50
	v_exp_f32_e32 v50, v50
	s_nop 0
	v_mul_f32_e32 v50, v51, v50
	v_mul_f32_e32 v50, v75, v50
	v_cndmask_b32_e64 v75, 0, v50, s[16:17]
	v_sub_f32_e32 v50, v218, v56
	v_sub_f32_e32 v51, v218, v57
	v_mul_f32_e32 v50, 0x3fb8aa3b, v50
	v_mul_f32_e32 v51, 0x3fb8aa3b, v51
	v_exp_f32_e32 v50, v50
	v_exp_f32_e32 v51, v51
	s_nop 0
	v_pk_mul_f32 v[50:51], v[52:53], v[50:51]
	s_nop 0
	v_pk_mul_f32 v[54:55], v[76:77], v[50:51]
	v_cvt_pk_bf16_f32 v51, v78, v79
	v_cvt_pk_bf16_f32 v53, v54, v55
	v_cndmask_b32_e64 v52, v51, 0, s[12:13]
	v_lshrrev_b32_e32 v51, 16, v51
	v_cndmask_b32_e64 v54, v53, 0, s[20:21]
	v_lshrrev_b32_e32 v53, 16, v53
	v_cndmask_b32_e64 v51, v51, 0, s[10:11]
	v_cndmask_b32_e64 v53, v53, 0, s[18:19]
	v_cvt_pk_bf16_f32 v50, v219, v220
	v_perm_b32 v51, v51, v52, s27
	v_cvt_pk_bf16_f32 v52, v74, v75
	v_perm_b32 v53, v53, v54, s27
	ds_read_b64_tr_b16 v[54:55], v138
	ds_read_b64_tr_b16 v[56:57], v139
	ds_read_b64_tr_b16 v[74:75], v140
	ds_read_b64_tr_b16 v[76:77], v141
	s_waitcnt lgkmcnt(0)
	s_nop 1
	v_mfma_f32_16x16x32_bf16 v[54:57], v[50:53], v[54:57], 0
	v_mfma_f32_16x16x32_bf16 v[50:53], v[50:53], v[74:77], 0
	s_cbranch_vccnz .LBB0_361
	ds_read_b128 v[74:77], v207 offset:8704
	ds_read_b128 v[78:81], v207 offset:8768
	s_andn2_b64 vcc, exec, s[40:41]
	s_waitcnt lgkmcnt(1)
	v_mfma_f32_16x16x32_bf16 v[74:77], v[74:77], v[66:69], 0
	s_waitcnt lgkmcnt(0)
	v_mfma_f32_16x16x32_bf16 v[74:77], v[78:81], v[62:65], v[74:77]
	ds_read_b128 v[78:81], v207 offset:8832
	s_waitcnt lgkmcnt(0)
	v_mfma_f32_16x16x32_bf16 v[74:77], v[78:81], v[58:61], v[74:77]
	ds_read_b128 v[78:81], v207 offset:8896
	s_waitcnt lgkmcnt(0)
	v_mfma_f32_16x16x32_bf16 v[78:81], v[78:81], v[70:73], v[74:77]
	s_nop 4
	v_mov_b32_e32 v74, 0
	v_mov_b32_e32 v75, 0
	v_mov_b32_e32 v76, 0
	v_mov_b32_e32 v77, 0
	s_cbranch_vccnz .LBB0_359
	v_add_u32_e32 v219, v133, v126
	ds_read_b128 v[74:77], v219 offset:13056
	ds_read_b128 v[220:223], v219 offset:13120
	s_waitcnt lgkmcnt(1)
	v_mfma_f32_16x16x32_bf16 v[74:77], v[74:77], v[66:69], 0
	s_waitcnt lgkmcnt(0)
	v_mfma_f32_16x16x32_bf16 v[74:77], v[220:223], v[62:65], v[74:77]
	ds_read_b128 v[220:223], v219 offset:13184
	s_waitcnt lgkmcnt(0)
	v_mfma_f32_16x16x32_bf16 v[74:77], v[220:223], v[58:61], v[74:77]
	ds_read_b128 v[220:223], v219 offset:13248
	s_waitcnt lgkmcnt(0)
	v_mfma_f32_16x16x32_bf16 v[74:77], v[220:223], v[70:73], v[74:77]
.LBB0_359:
	ds_read_b128 v[220:223], v142
	ds_read_b128 v[224:227], v143
	v_readlane_b32 s24, v242, 13
	v_readlane_b32 s25, v242, 14
	s_waitcnt lgkmcnt(1)
	v_sub_f32_e32 v219, v218, v220
	v_mul_f32_e32 v219, 0x3fb8aa3b, v219
	v_exp_f32_e32 v219, v219
	s_nop 0
	v_mul_f32_e32 v78, v78, v219
	s_waitcnt lgkmcnt(0)
	v_mul_f32_e32 v78, v224, v78
	v_cndmask_b32_e64 v219, v78, 0, s[30:31]
	v_sub_f32_e32 v78, v218, v221
	v_mul_f32_e32 v78, 0x3fb8aa3b, v78
	v_exp_f32_e32 v78, v78
	s_nop 0
	v_mul_f32_e32 v78, v79, v78
	v_mul_f32_e32 v78, v225, v78
	v_cndmask_b32_e64 v228, 0, v78, s[34:35]
	v_sub_f32_e32 v78, v218, v222
	v_sub_f32_e32 v79, v218, v223
	v_mul_f32_e32 v78, 0x3fb8aa3b, v78
	v_mul_f32_e32 v79, 0x3fb8aa3b, v79
	v_exp_f32_e32 v78, v78
	v_exp_f32_e32 v79, v79
	s_nop 0
	v_pk_mul_f32 v[78:79], v[80:81], v[78:79]
	s_nop 0
	v_pk_mul_f32 v[224:225], v[226:227], v[78:79]
	ds_read_b128 v[78:81], v144
	ds_read_b128 v[220:223], v145
	s_waitcnt lgkmcnt(1)
	v_sub_f32_e32 v78, v218, v78
	v_mul_f32_e32 v78, 0x3fb8aa3b, v78
	v_exp_f32_e32 v78, v78
	s_nop 0
	v_mul_f32_e32 v74, v74, v78
	s_waitcnt lgkmcnt(0)
	v_mul_f32_e32 v74, v220, v74
	v_cndmask_b32_e64 v220, v74, 0, s[72:73]
	v_sub_f32_e32 v74, v218, v79
	v_mul_f32_e32 v74, 0x3fb8aa3b, v74
	v_exp_f32_e32 v74, v74
	s_nop 0
	v_mul_f32_e32 v74, v75, v74
	v_mul_f32_e32 v74, v221, v74
	v_cndmask_b32_e64 v221, 0, v74, s[56:57]
	v_sub_f32_e32 v74, v218, v80
	v_sub_f32_e32 v75, v218, v81
	v_mul_f32_e32 v74, 0x3fb8aa3b, v74
	v_mul_f32_e32 v75, 0x3fb8aa3b, v75
	v_exp_f32_e32 v74, v74
	v_exp_f32_e32 v75, v75
	s_nop 0
	v_pk_mul_f32 v[74:75], v[76:77], v[74:75]
	s_nop 0
	v_pk_mul_f32 v[78:79], v[222:223], v[74:75]
	v_cvt_pk_bf16_f32 v75, v224, v225
	v_cvt_pk_bf16_f32 v77, v78, v79
	v_cndmask_b32_e64 v76, v75, 0, s[54:55]
	v_lshrrev_b32_e32 v75, 16, v75
	v_cndmask_b32_e64 v78, v77, 0, s[24:25]
	v_lshrrev_b32_e32 v77, 16, v77
	v_cndmask_b32_e64 v75, v75, 0, s[42:43]
	v_cndmask_b32_e64 v77, v77, 0, s[58:59]
	v_cvt_pk_bf16_f32 v74, v219, v228
	v_perm_b32 v75, v75, v76, s27
	v_cvt_pk_bf16_f32 v76, v220, v221
	v_perm_b32 v77, v77, v78, s27
	ds_read_b64_tr_b16 v[78:79], v146
	ds_read_b64_tr_b16 v[80:81], v147
	s_waitcnt lgkmcnt(0)
	s_nop 1
	v_mfma_f32_16x16x32_bf16 v[54:57], v[74:77], v[78:81], v[54:57]
	ds_read_b64_tr_b16 v[78:79], v148
	ds_read_b64_tr_b16 v[80:81], v149
	s_waitcnt lgkmcnt(0)
	s_nop 0
	v_mfma_f32_16x16x32_bf16 v[50:53], v[74:77], v[78:81], v[50:53]
	s_andn2_b64 vcc, exec, s[2:3]
	s_cbranch_vccz .LBB0_362

.LBB0_364:
	ds_read_b128 v[220:223], v150
	ds_read_b128 v[224:227], v151
	v_readlane_b32 s24, v242, 26
	v_readlane_b32 s25, v242, 27
	s_waitcnt lgkmcnt(1)
	v_sub_f32_e32 v219, v218, v220
	v_mul_f32_e32 v219, 0x3fb8aa3b, v219
	v_exp_f32_e32 v219, v219
	s_nop 0
	v_mul_f32_e32 v78, v78, v219
	s_waitcnt lgkmcnt(0)
	v_mul_f32_e32 v78, v224, v78
	v_cndmask_b32_e64 v219, v78, 0, s[24:25]
	v_sub_f32_e32 v78, v218, v221
	v_mul_f32_e32 v78, 0x3fb8aa3b, v78
	v_exp_f32_e32 v78, v78
	v_readlane_b32 s24, v242, 28
	v_readlane_b32 s25, v242, 29
	v_mul_f32_e32 v78, v79, v78
	v_mul_f32_e32 v78, v225, v78
	v_cndmask_b32_e64 v228, 0, v78, s[24:25]
	v_sub_f32_e32 v78, v218, v222
	v_sub_f32_e32 v79, v218, v223
	v_mul_f32_e32 v78, 0x3fb8aa3b, v78
	v_mul_f32_e32 v79, 0x3fb8aa3b, v79
	v_exp_f32_e32 v78, v78
	v_exp_f32_e32 v79, v79
	v_readlane_b32 s24, v242, 34
	v_readlane_b32 s25, v242, 35
	v_pk_mul_f32 v[78:79], v[80:81], v[78:79]
	s_nop 0
	v_pk_mul_f32 v[224:225], v[226:227], v[78:79]
	ds_read_b128 v[78:81], v152
	ds_read_b128 v[220:223], v153
	s_waitcnt lgkmcnt(1)
	v_sub_f32_e32 v78, v218, v78
	v_mul_f32_e32 v78, 0x3fb8aa3b, v78
	v_exp_f32_e32 v78, v78
	s_nop 0
	v_mul_f32_e32 v74, v74, v78
	s_waitcnt lgkmcnt(0)
	v_mul_f32_e32 v74, v220, v74
	v_cndmask_b32_e64 v220, v74, 0, s[24:25]
	v_sub_f32_e32 v74, v218, v79
	v_mul_f32_e32 v74, 0x3fb8aa3b, v74
	v_exp_f32_e32 v74, v74
	v_readlane_b32 s24, v242, 36
	v_readlane_b32 s25, v242, 37
	v_mul_f32_e32 v74, v75, v74
	v_mul_f32_e32 v74, v221, v74
	v_cndmask_b32_e64 v221, 0, v74, s[24:25]
	v_sub_f32_e32 v74, v218, v80
	v_sub_f32_e32 v75, v218, v81
	v_mul_f32_e32 v74, 0x3fb8aa3b, v74
	v_mul_f32_e32 v75, 0x3fb8aa3b, v75
	v_exp_f32_e32 v74, v74
	v_exp_f32_e32 v75, v75
	v_readlane_b32 s24, v242, 32
	v_readlane_b32 s25, v242, 33
	v_pk_mul_f32 v[74:75], v[76:77], v[74:75]
	s_nop 0
	v_pk_mul_f32 v[78:79], v[222:223], v[74:75]
	v_cvt_pk_bf16_f32 v75, v224, v225
	v_cndmask_b32_e64 v76, v75, 0, s[24:25]
	v_readlane_b32 s24, v242, 30
	v_lshrrev_b32_e32 v75, 16, v75
	v_readlane_b32 s25, v242, 31
	v_cvt_pk_bf16_f32 v77, v78, v79
	v_cvt_pk_bf16_f32 v74, v219, v228
	v_cndmask_b32_e64 v75, v75, 0, s[24:25]
	v_readlane_b32 s24, v242, 40
	v_readlane_b32 s25, v242, 41
	v_perm_b32 v75, v75, v76, s27
	v_cvt_pk_bf16_f32 v76, v220, v221
	v_cndmask_b32_e64 v78, v77, 0, s[24:25]
	v_readlane_b32 s24, v242, 38
	v_lshrrev_b32_e32 v77, 16, v77
	v_readlane_b32 s25, v242, 39
	s_nop 1
	v_cndmask_b32_e64 v77, v77, 0, s[24:25]
	v_perm_b32 v77, v77, v78, s27
	ds_read_b64_tr_b16 v[78:79], v154
	ds_read_b64_tr_b16 v[80:81], v155
	s_waitcnt lgkmcnt(0)
	s_nop 1
	v_mfma_f32_16x16x32_bf16 v[54:57], v[74:77], v[78:81], v[54:57]
	ds_read_b64_tr_b16 v[78:79], v156
	ds_read_b64_tr_b16 v[80:81], v157
	s_waitcnt lgkmcnt(0)
	s_nop 0
	v_mfma_f32_16x16x32_bf16 v[50:53], v[74:77], v[78:81], v[50:53]
	s_andn2_b64 vcc, exec, s[82:83]
	s_cbranch_vccnz .LBB0_368

.LBB0_367:
	ds_read_b128 v[220:223], v158
	ds_read_b128 v[224:227], v159
	v_readlane_b32 s24, v242, 45
	v_readlane_b32 s25, v242, 46
	s_waitcnt lgkmcnt(1)
	v_sub_f32_e32 v219, v218, v220
	v_mul_f32_e32 v219, 0x3fb8aa3b, v219
	v_exp_f32_e32 v219, v219
	s_nop 0
	v_mul_f32_e32 v78, v78, v219
	s_waitcnt lgkmcnt(0)
	v_mul_f32_e32 v78, v224, v78
	v_cndmask_b32_e64 v219, v78, 0, s[24:25]
	v_sub_f32_e32 v78, v218, v221
	v_mul_f32_e32 v78, 0x3fb8aa3b, v78
	v_exp_f32_e32 v78, v78
	v_readlane_b32 s24, v242, 47
	v_readlane_b32 s25, v242, 48
	v_mul_f32_e32 v78, v79, v78
	v_mul_f32_e32 v78, v225, v78
	v_cndmask_b32_e64 v228, 0, v78, s[24:25]
	v_sub_f32_e32 v78, v218, v222
	v_sub_f32_e32 v79, v218, v223
	v_mul_f32_e32 v78, 0x3fb8aa3b, v78
	v_mul_f32_e32 v79, 0x3fb8aa3b, v79
	v_exp_f32_e32 v78, v78
	v_exp_f32_e32 v79, v79
	v_readlane_b32 s24, v242, 49
	v_readlane_b32 s25, v242, 50
	v_pk_mul_f32 v[78:79], v[80:81], v[78:79]
	s_nop 0
	v_pk_mul_f32 v[224:225], v[226:227], v[78:79]
	ds_read_b128 v[78:81], v160
	ds_read_b128 v[220:223], v161
	s_waitcnt lgkmcnt(1)
	v_sub_f32_e32 v78, v218, v78
	v_mul_f32_e32 v78, 0x3fb8aa3b, v78
	v_exp_f32_e32 v78, v78
	s_nop 0
	v_mul_f32_e32 v74, v74, v78
	s_waitcnt lgkmcnt(0)
	v_mul_f32_e32 v74, v220, v74
	v_cndmask_b32_e64 v220, v74, 0, s[64:65]
	v_sub_f32_e32 v74, v218, v79
	v_mul_f32_e32 v74, 0x3fb8aa3b, v74
	v_exp_f32_e32 v74, v74
	s_nop 0
	v_mul_f32_e32 v74, v75, v74
	v_mul_f32_e32 v74, v221, v74
	v_cndmask_b32_e64 v221, 0, v74, s[66:67]
	v_sub_f32_e32 v74, v218, v80
	v_sub_f32_e32 v75, v218, v81
	v_mul_f32_e32 v74, 0x3fb8aa3b, v74
	v_mul_f32_e32 v75, 0x3fb8aa3b, v75
	v_exp_f32_e32 v74, v74
	v_exp_f32_e32 v75, v75
	s_nop 0
	v_pk_mul_f32 v[74:75], v[76:77], v[74:75]
	s_nop 0
	v_pk_mul_f32 v[78:79], v[222:223], v[74:75]
	v_cvt_pk_bf16_f32 v75, v224, v225
	v_cvt_pk_bf16_f32 v77, v78, v79
	v_cndmask_b32_e64 v76, v75, 0, s[62:63]
	v_lshrrev_b32_e32 v75, 16, v75
	v_cndmask_b32_e64 v78, v77, 0, s[70:71]
	v_lshrrev_b32_e32 v77, 16, v77
	v_cndmask_b32_e64 v75, v75, 0, s[24:25]
	v_cndmask_b32_e64 v77, v77, 0, s[68:69]
	v_cvt_pk_bf16_f32 v74, v219, v228
	v_perm_b32 v75, v75, v76, s27
	v_cvt_pk_bf16_f32 v76, v220, v221
	v_perm_b32 v77, v77, v78, s27
	ds_read_b64_tr_b16 v[78:79], v162
	ds_read_b64_tr_b16 v[80:81], v163
	s_waitcnt lgkmcnt(0)
	s_nop 1
	v_mfma_f32_16x16x32_bf16 v[54:57], v[74:77], v[78:81], v[54:57]
	ds_read_b64_tr_b16 v[78:79], v164
	ds_read_b64_tr_b16 v[80:81], v165
	s_waitcnt lgkmcnt(0)
	s_nop 0
	v_mfma_f32_16x16x32_bf16 v[50:53], v[74:77], v[78:81], v[50:53]

.LBB0_376:
	s_or_b64 exec, exec, s[24:25]
	s_waitcnt lgkmcnt(0)
	s_barrier
	v_mov_b32_e32 v50, s28
	ds_read_b32 v50, v50
	s_andn2_b64 vcc, exec, s[22:23]
	s_waitcnt lgkmcnt(0)
	v_mul_f32_e32 v50, 0x3fb8aa3b, v50
	v_exp_f32_e32 v52, v50
	ds_read_b64_tr_b16 v[212:213], v176
	ds_read_b64_tr_b16 v[214:215], v177
	ds_read_b64_tr_b16 v[216:217], v178
	ds_read_b64_tr_b16 v[218:219], v179
	ds_read_b64_tr_b16 v[220:221], v180
	ds_read_b64_tr_b16 v[222:223], v181
	ds_read_b64_tr_b16 v[224:225], v182
	ds_read_b64_tr_b16 v[226:227], v183
	ds_read_b64_tr_b16 v[228:229], v184
	ds_read_b64_tr_b16 v[230:231], v185
	ds_read_b64_tr_b16 v[232:233], v186
	ds_read_b64_tr_b16 v[234:235], v187
	v_pk_mul_f32 v[24:25], v[24:25], v[52:53] op_sel_hi:[1,0]
	v_pk_mul_f32 v[22:23], v[22:23], v[52:53] op_sel_hi:[1,0]
	v_pk_mul_f32 v[48:49], v[48:49], v[52:53] op_sel_hi:[1,0]
	v_pk_mul_f32 v[46:47], v[46:47], v[52:53] op_sel_hi:[1,0]
	s_waitcnt lgkmcnt(8)
	v_mfma_f32_16x16x32_bf16 v[22:25], v[216:219], v[212:215], v[22:25]
	s_waitcnt lgkmcnt(6)
	v_mfma_f32_16x16x32_bf16 v[46:49], v[220:223], v[212:215], v[46:49]
	s_waitcnt lgkmcnt(2)
	v_mfma_f32_16x16x32_bf16 v[22:25], v[228:231], v[224:227], v[22:25]
	s_waitcnt lgkmcnt(0)
	v_mfma_f32_16x16x32_bf16 v[46:49], v[232:235], v[224:227], v[46:49]
	ds_read_b64_tr_b16 v[212:213], v188
	ds_read_b64_tr_b16 v[214:215], v189
	ds_read_b64_tr_b16 v[216:217], v190
	ds_read_b64_tr_b16 v[218:219], v191
	ds_read_b64_tr_b16 v[220:221], v192
	ds_read_b64_tr_b16 v[222:223], v193
	ds_read_b64_tr_b16 v[224:225], v194
	ds_read_b64_tr_b16 v[226:227], v195
	ds_read_b64_tr_b16 v[228:229], v196
	ds_read_b64_tr_b16 v[230:231], v197
	ds_read_b64_tr_b16 v[232:233], v198
	ds_read_b64_tr_b16 v[234:235], v199
	s_waitcnt lgkmcnt(8)
	v_mfma_f32_16x16x32_bf16 v[22:25], v[216:219], v[212:215], v[22:25]
	s_waitcnt lgkmcnt(6)
	v_mfma_f32_16x16x32_bf16 v[46:49], v[220:223], v[212:215], v[46:49]
	s_waitcnt lgkmcnt(2)
	v_mfma_f32_16x16x32_bf16 v[22:25], v[228:231], v[224:227], v[22:25]
	s_waitcnt lgkmcnt(0)
	v_mfma_f32_16x16x32_bf16 v[46:49], v[232:235], v[224:227], v[46:49]
	s_nop 5
	v_cvt_pk_bf16_f32 v50, v22, s0
	ds_write_b16 v205, v50
	v_cvt_pk_bf16_f32 v50, v23, s0
	ds_write_b16 v205, v50 offset:272
	v_cvt_pk_bf16_f32 v50, v24, s0
	ds_write_b16 v205, v50 offset:544
	v_cvt_pk_bf16_f32 v50, v25, s0
	ds_write_b16 v206, v50
	v_cvt_pk_bf16_f32 v50, v46, s0
	ds_write_b16 v205, v50 offset:4352
	v_cvt_pk_bf16_f32 v50, v47, s0
	ds_write_b16 v205, v50 offset:4624
	v_cvt_pk_bf16_f32 v50, v48, s0
	ds_write_b16 v205, v50 offset:4896
	v_cvt_pk_bf16_f32 v50, v49, s0
	ds_write_b16 v205, v50 offset:5168
	s_cbranch_vccnz .LBB0_349
	global_store_dword v[100:101], v22, off
	global_store_dword v[102:103], v23, off
	global_store_dword v[104:105], v24, off
	global_store_dword v[106:107], v25, off
	global_store_dword v[108:109], v46, off
	global_store_dword v[110:111], v47, off
	global_store_dword v[112:113], v48, off
	global_store_dword v[114:115], v49, off
	s_branch .LBB0_349
